# speedup vs baseline: 1.0583x; 1.0072x over previous
;     ...
;       {
;         const int ck = tid & 15;
;         const int ch = chb + ck * 8;
;         float w0[2][8], w1[2][8], w2[2][8], bb[2][8];
; #pragma unroll
;         for (int h = 0; h < 2; ++h) {
;           ld8f(p->w_conv + ch + h * DFF, w0[h]); ld8f(p->w_conv + UPW + ch + h * DFF, w1[h]);
;           ld8f(p->w_conv + 2 * UPW + ch + h * DFF, w2[h]); ld8f(p->b_conv + ch + h * DFF, bb[h]);
;         }
;         u16* FI = (u16*)(wsl + w_fi);
; #pragma unroll 2
;         for (int i = 0; i < 8; ++i) {
;           const int row = (tid >> 4) + i * 32;
;           const int rg = g0 + cur_brow + row;
;           int t, b; const bool samp = rg >= NPROMPT;
;           if (!samp) { t = rg & (SEQ - 1); b = rg >> 11; } else { const int rs = rg - NPROMPT; t = rs & (DSEQ - 1); b = rs >> 6; }
;           if (t >= 2 && row < 2) continue;
.LBB0_1148:
	s_or_b64 exec, exec, s[2:3]
	s_cmp_lt_i32 s85, 0x10000
	s_cselect_b32 s2, 1, 0
	s_and_b32 s3, s85, 0x7ff
	s_cmp_lg_u32 s3, 0
	s_cselect_b32 s3, 1, 0
	s_and_b32 s2, s2, s3
	s_cmp_lg_u32 s2, 0
	s_cbranch_scc1 .Lupc_fast_p
	s_load_dwordx4 s[4:7], s[0:1], 0x98
	v_lshl_or_b32 v106, v148, 3, s60
	v_ashrrev_i32_e32 v107, 31, v106
	v_lshlrev_b64 v[2:3], 2, v[106:107]
	s_mov_b64 s[2:3], 0x5800
	s_waitcnt lgkmcnt(0)
	v_lshl_add_u64 v[50:51], s[4:5], 0, v[2:3]
	v_lshl_add_u64 v[18:19], v[50:51], 0, s[2:3]
	s_mov_b64 s[2:3], 0xb000
	v_lshl_add_u64 v[22:23], v[50:51], 0, s[2:3]
	s_mov_b64 s[2:3], 0x8400
	v_lshl_add_u64 v[46:47], v[50:51], 0, s[2:3]
	s_mov_b64 s[2:3], 0xdc00
	v_lshl_add_u64 v[54:55], v[50:51], 0, s[2:3]
	s_movk_i32 s2, 0x5000
	v_add_co_u32_e32 v10, vcc, s2, v50
	s_mov_b32 s2, 0x8000
	s_nop 0
	v_addc_co_u32_e32 v11, vcc, 0, v51, vcc
	v_add_co_u32_e32 v14, vcc, s81, v50
	v_lshl_add_u64 v[58:59], s[6:7], 0, v[2:3]
	s_nop 0
	v_addc_co_u32_e32 v15, vcc, 0, v51, vcc
	v_add_co_u32_e32 v34, vcc, s80, v50
	v_lshl_add_u64 v[42:43], v[50:51], 0, s[88:89]
	s_nop 0
	v_addc_co_u32_e32 v35, vcc, 0, v51, vcc
	v_add_co_u32_e32 v38, vcc, s2, v50
	s_mov_b32 s2, 0xd000
	s_nop 0
	v_addc_co_u32_e32 v39, vcc, 0, v51, vcc
	global_load_dwordx4 v[2:5], v[50:51], off offset:16
	global_load_dwordx4 v[6:9], v[50:51], off
	s_nop 0
	global_load_dwordx4 v[10:13], v[10:11], off offset:2048
	s_nop 0
	global_load_dwordx4 v[14:17], v[14:15], off
	s_nop 0
	global_load_dwordx4 v[18:21], v[18:19], off offset:16
	s_nop 0
	global_load_dwordx4 v[22:25], v[22:23], off offset:16
	s_nop 0
	global_load_dwordx4 v[26:29], v[58:59], off offset:16
	global_load_dwordx4 v[30:33], v[58:59], off
	v_add_co_u32_e32 v50, vcc, s2, v50
	v_lshl_add_u64 v[62:63], v[58:59], 0, s[88:89]
	s_nop 0
	v_addc_co_u32_e32 v51, vcc, 0, v51, vcc
	global_load_dwordx4 v[34:37], v[34:35], off offset:3072
	s_nop 0
	global_load_dwordx4 v[38:41], v[38:39], off offset:1024
	s_nop 0
	global_load_dwordx4 v[42:45], v[42:43], off offset:16
	s_nop 0
	global_load_dwordx4 v[46:49], v[46:47], off offset:16
	v_add_co_u32_e32 v58, vcc, s80, v58
	global_load_dwordx4 v[50:53], v[50:51], off offset:3072
	s_nop 0
	global_load_dwordx4 v[54:57], v[54:55], off offset:16
	v_addc_co_u32_e32 v59, vcc, 0, v59, vcc
	global_load_dwordx4 v[58:61], v[58:59], off offset:3072
	s_nop 0
	global_load_dwordx4 v[62:65], v[62:63], off offset:16
	v_ashrrev_i32_e32 v112, 4, v149
	v_lshl_add_u64 v[66:67], v[106:107], 1, s[74:75]
	s_mov_b64 s[2:3], 0x1aac0000
	v_lshl_add_u64 v[108:109], v[66:67], 0, s[2:3]
	v_add_u32_e32 v66, -1, v112
	v_bitop3_b32 v68, v112, v148, 31 bitop3:0x6c
	v_add_u32_e32 v67, 30, v112
	v_lshlrev_b32_e32 v113, 4, v68
	v_bitop3_b32 v68, v66, v148, 31 bitop3:0x6c
	v_bitop3_b32 v66, v66, v120, 31 bitop3:0x6c
	v_lshlrev_b32_e32 v114, 4, v68
	v_bitop3_b32 v68, v67, v148, 31 bitop3:0x6c
	v_lshlrev_b32_e32 v117, 4, v66
	v_bitop3_b32 v66, v67, v120, 31 bitop3:0x6c
	v_lshlrev_b32_e32 v115, 4, v68
	v_bitop3_b32 v68, v120, v112, 31 bitop3:0x78
	v_lshlrev_b32_e32 v118, 4, v66
	v_add_u32_e32 v119, s86, v112
	v_xad_u32 v66, s86, 32, v112
	s_add_i32 s2, s69, s86
	s_mov_b32 s14, 0
	v_lshlrev_b32_e32 v116, 4, v68
	v_and_b32_e32 v120, 63, v119
	v_and_b32_e32 v121, 63, v66
	v_lshl_add_u32 v122, v112, 9, v209
	v_add_u32_e32 v123, s2, v112
	s_branch .LBB0_1151

;     ...
;         float w0[2][8], w1[2][8], w2[2][8], bb[2][8];
; #pragma unroll
;         for (int h = 0; h < 2; ++h) {
;           ld8f(p->w_conv + ch + h * DFF, w0[h]); ld8f(p->w_conv + UPW + ch + h * DFF, w1[h]);
;           ld8f(p->w_conv + 2 * UPW + ch + h * DFF, w2[h]); ld8f(p->b_conv + ch + h * DFF, bb[h]);
;         }
;         u16* FI = (u16*)(wsl + w_fi);
; #pragma unroll 2
;         for (int i = 0; i < 8; ++i) {
;           const int row = (tid >> 4) + i * 32;
;           const int rg = g0 + cur_brow + row;
;           int t, b; const bool samp = rg >= NPROMPT;
;           if (!samp) { t = rg & (SEQ - 1); b = rg >> 11; } else { const int rs = rg - NPROMPT; t = rs & (DSEQ - 1); b = rs >> 6; }
;           if (t >= 2 && row < 2) continue;
;           float res[8];
; #pragma unroll
;           for (int h = 0; h < 2; ++h) {
;             const int c16 = h * 16 + ck;
;             float cur[8], p1[8], p2[8];
;             ld8(reinterpret_cast<const u16*>(st + row * 512 + ((c16 ^ (row & 31)) << 4)), cur);
;             if (t >= 1) ld8(reinterpret_cast<const u16*>(st + (row - 1) * 512 + ((c16 ^ ((row - 1) & 31)) << 4)), p1);
;             else if (samp) ld8f(p->cstate + ((size_t)b * 2 + 1) * UPW + ch + h * DFF, p1);
;             else { for (int k = 0; k < 8; ++k) p1[k] = 0.f; }
;             if (t >= 2) ld8(reinterpret_cast<const u16*>(st + (row - 2) * 512 + ((c16 ^ ((row - 2) & 31)) << 4)), p2);
;             else if (samp) ld8f(p->cstate + ((size_t)b * 2 + t) * UPW + ch + h * DFF, p2);
;             else { for (int k = 0; k < 8; ++k) p2[k] = 0.f; }
.Lupc_fast_p:
	s_load_dwordx4 s[4:7], s[0:1], 0x98
	v_and_b32_e32 v140, 15, v149
	v_lshrrev_b32_e32 v141, 4, v149
	s_lshr_b32 s20, s70, 1
	s_and_b32 s20, s20, 0xffffff80
	v_lshlrev_b32_e32 v142, 3, v141
	v_lshl_add_u32 v143, v140, 3, s20
	v_lshlrev_b32_e32 v143, 2, v143
	s_waitcnt lgkmcnt(0)
	s_add_u32 s8, s4, 0x2c00
	s_addc_u32 s9, s5, 0
	s_add_u32 s10, s4, 0x5800
	s_addc_u32 s11, s5, 0
	s_add_u32 s12, s4, 0x8400
	s_addc_u32 s13, s5, 0
	s_add_u32 s14, s4, 0xb000
	s_addc_u32 s15, s5, 0
	s_add_u32 s16, s4, 0xdc00
	s_addc_u32 s17, s5, 0
	s_add_u32 s18, s6, 0x2c00
	s_addc_u32 s19, s7, 0
	global_load_dwordx4 v[2:5], v143, s[4:5]
	global_load_dwordx4 v[6:9], v143, s[4:5] offset:16
	global_load_dwordx4 v[10:13], v143, s[8:9]
	global_load_dwordx4 v[14:17], v143, s[8:9] offset:16
	global_load_dwordx4 v[18:21], v143, s[10:11]
	global_load_dwordx4 v[22:25], v143, s[10:11] offset:16
	global_load_dwordx4 v[26:29], v143, s[12:13]
	global_load_dwordx4 v[30:33], v143, s[12:13] offset:16
	global_load_dwordx4 v[34:37], v143, s[14:15]
	global_load_dwordx4 v[38:41], v143, s[14:15] offset:16
	global_load_dwordx4 v[42:45], v143, s[16:17]
	global_load_dwordx4 v[46:49], v143, s[16:17] offset:16
	global_load_dwordx4 v[50:53], v143, s[6:7]
	global_load_dwordx4 v[54:57], v143, s[6:7] offset:16
	global_load_dwordx4 v[58:61], v143, s[18:19]
	global_load_dwordx4 v[62:65], v143, s[18:19] offset:16
	s_mul_i32 s2, s86, 0x1600
	s_lshl_b32 s3, s20, 1
	s_add_u32 s2, s2, s3
	s_add_u32 s2, s2, 0x1aac0000
	s_add_u32 s2, s74, s2
	s_addc_u32 s3, s75, 0
	v_mul_u32_u24_e32 v144, 0x1600, v142
	v_lshl_add_u32 v144, v140, 4, v144
	s_mov_b32 s21, 0xffff0000
	s_mov_b32 s22, 0xbdd2d3e7
	v_cmp_lt_u32_e64 s[58:59], 15, v149
	v_add_u32_e32 v145, -2, v142
	v_max_i32_e32 v145, 0, v145
	v_and_b32_e32 v146, 31, v145
	v_xor_b32_e32 v146, v146, v140
	v_lshlrev_b32_e32 v146, 4, v146
	v_lshl_or_b32 v146, v145, 9, v146
	v_xor_b32_e32 v147, 0x100, v146
	ds_read_b128 v[114:117], v146
	ds_read_b128 v[118:121], v147
	v_add_u32_e32 v145, -1, v142
	v_max_i32_e32 v145, 0, v145
	v_and_b32_e32 v146, 31, v145
	v_xor_b32_e32 v146, v146, v140
	v_lshlrev_b32_e32 v146, 4, v146
	v_lshl_or_b32 v146, v145, 9, v146
	v_xor_b32_e32 v147, 0x100, v146
	ds_read_b128 v[222:225], v146
	ds_read_b128 v[226:229], v147
	s_waitcnt lgkmcnt(2)
	v_lshlrev_b32_e32 v66, 16, v114
	v_and_b32_e32 v67, s21, v114
	v_lshlrev_b32_e32 v68, 16, v115
	v_and_b32_e32 v69, s21, v115
	v_lshlrev_b32_e32 v70, 16, v116
	v_and_b32_e32 v71, s21, v116
	v_lshlrev_b32_e32 v72, 16, v117
	v_and_b32_e32 v73, s21, v117
	v_lshlrev_b32_e32 v74, 16, v118
	v_and_b32_e32 v75, s21, v118
	v_lshlrev_b32_e32 v76, 16, v119
	v_and_b32_e32 v77, s21, v119
	v_lshlrev_b32_e32 v78, 16, v120
	v_and_b32_e32 v79, s21, v120
	v_lshlrev_b32_e32 v80, 16, v121
	v_and_b32_e32 v81, s21, v121
	v_mov_b32_e32 v145, v142
	v_and_b32_e32 v146, 31, v145
	v_xor_b32_e32 v146, v146, v140
	v_lshlrev_b32_e32 v146, 4, v146
	v_lshl_or_b32 v146, v145, 9, v146
	v_xor_b32_e32 v147, 0x100, v146
	ds_read_b128 v[114:117], v146
	ds_read_b128 v[118:121], v147
	s_waitcnt lgkmcnt(2)
	v_lshlrev_b32_e32 v82, 16, v222
	v_and_b32_e32 v83, s21, v222
	v_lshlrev_b32_e32 v84, 16, v223
	v_and_b32_e32 v85, s21, v223
	v_lshlrev_b32_e32 v86, 16, v224
	v_and_b32_e32 v87, s21, v224
	v_lshlrev_b32_e32 v88, 16, v225
	v_and_b32_e32 v89, s21, v225
	v_lshlrev_b32_e32 v90, 16, v226
	v_and_b32_e32 v91, s21, v226
	v_lshlrev_b32_e32 v92, 16, v227
	v_and_b32_e32 v93, s21, v227
	v_lshlrev_b32_e32 v94, 16, v228
	v_and_b32_e32 v95, s21, v228
	v_lshlrev_b32_e32 v96, 16, v229
	v_and_b32_e32 v97, s21, v229
	v_add_u32_e32 v145, 1, v142
	v_and_b32_e32 v146, 31, v145
	v_xor_b32_e32 v146, v146, v140
	v_lshlrev_b32_e32 v146, 4, v146
	v_lshl_or_b32 v146, v145, 9, v146
	v_xor_b32_e32 v147, 0x100, v146
	ds_read_b128 v[222:225], v146
	ds_read_b128 v[226:229], v147
	s_waitcnt lgkmcnt(2)
	v_lshlrev_b32_e32 v98, 16, v114
	v_and_b32_e32 v99, s21, v114
	v_lshlrev_b32_e32 v100, 16, v115
	v_and_b32_e32 v101, s21, v115
	v_lshlrev_b32_e32 v102, 16, v116
	v_and_b32_e32 v103, s21, v116
	v_lshlrev_b32_e32 v104, 16, v117
	v_and_b32_e32 v105, s21, v117
	v_lshlrev_b32_e32 v106, 16, v118
	v_and_b32_e32 v107, s21, v118
	v_lshlrev_b32_e32 v108, 16, v119
	v_and_b32_e32 v109, s21, v119
	v_lshlrev_b32_e32 v110, 16, v120
	v_and_b32_e32 v111, s21, v120
	v_lshlrev_b32_e32 v112, 16, v121
	v_and_b32_e32 v113, s21, v121
	v_add_u32_e32 v145, 2, v142
	v_and_b32_e32 v146, 31, v145
	v_xor_b32_e32 v146, v146, v140
	v_lshlrev_b32_e32 v146, 4, v146
	v_lshl_or_b32 v146, v145, 9, v146
	v_xor_b32_e32 v147, 0x100, v146
	ds_read_b128 v[114:117], v146
	ds_read_b128 v[118:121], v147
	s_waitcnt vmcnt(0)
; #define GAS __attribute__((address_space(1)))
;     ...
;           for (int h = 0; h < 2; ++h) {
;             const int c16 = h * 16 + ck;
;             float cur[8], p1[8], p2[8];
;             ld8(reinterpret_cast<const u16*>(st + row * 512 + ((c16 ^ (row & 31)) << 4)), cur);
;             if (t >= 1) ld8(reinterpret_cast<const u16*>(st + (row - 1) * 512 + ((c16 ^ ((row - 1) & 31)) << 4)), p1);
;             else if (samp) ld8f(p->cstate + ((size_t)b * 2 + 1) * UPW + ch + h * DFF, p1);
;             else { for (int k = 0; k < 8; ++k) p1[k] = 0.f; }
;             if (t >= 2) ld8(reinterpret_cast<const u16*>(st + (row - 2) * 512 + ((c16 ^ ((row - 2) & 31)) << 4)), p2);
;             else if (samp) ld8f(p->cstate + ((size_t)b * 2 + t) * UPW + ch + h * DFF, p2);
;             else { for (int k = 0; k < 8; ++k) p2[k] = 0.f; }
; #pragma unroll
;             for (int k = 0; k < 8; ++k) {
;               float cv = bb[h][k] + w0[h][k] * p2[k] + w1[h][k] * p1[k] + w2[h][k] * cur[k];
;               if (h == 0) res[k] = gelu_f(cv); else res[k] *= cv;
;             }
;           }
;           *(GAS uint4*)(FI + (size_t)(cur_brow + row) * DFF + ch) =
;               make_uint4(pack2(res[0], res[1]), pack2(res[2], res[3]), pack2(res[4], res[5]), pack2(res[6], res[7]));
	v_pk_fma_f32 v[122:123], v[2:3], v[66:67], v[50:51]
	v_pk_fma_f32 v[124:125], v[4:5], v[68:69], v[52:53]
	v_pk_fma_f32 v[126:127], v[6:7], v[70:71], v[54:55]
	v_pk_fma_f32 v[128:129], v[8:9], v[72:73], v[56:57]
	v_pk_fma_f32 v[214:215], v[10:11], v[74:75], v[58:59]
	v_pk_fma_f32 v[216:217], v[12:13], v[76:77], v[60:61]
	v_pk_fma_f32 v[218:219], v[14:15], v[78:79], v[62:63]
	v_pk_fma_f32 v[220:221], v[16:17], v[80:81], v[64:65]
	v_pk_fma_f32 v[122:123], v[18:19], v[82:83], v[122:123]
	v_pk_fma_f32 v[124:125], v[20:21], v[84:85], v[124:125]
	v_pk_fma_f32 v[126:127], v[22:23], v[86:87], v[126:127]
	v_pk_fma_f32 v[128:129], v[24:25], v[88:89], v[128:129]
	v_pk_fma_f32 v[214:215], v[26:27], v[90:91], v[214:215]
	v_pk_fma_f32 v[216:217], v[28:29], v[92:93], v[216:217]
	v_pk_fma_f32 v[218:219], v[30:31], v[94:95], v[218:219]
	v_pk_fma_f32 v[220:221], v[32:33], v[96:97], v[220:221]
	v_pk_fma_f32 v[122:123], v[34:35], v[98:99], v[122:123]
	v_pk_fma_f32 v[124:125], v[36:37], v[100:101], v[124:125]
	v_pk_fma_f32 v[126:127], v[38:39], v[102:103], v[126:127]
	v_pk_fma_f32 v[128:129], v[40:41], v[104:105], v[128:129]
	v_pk_fma_f32 v[214:215], v[42:43], v[106:107], v[214:215]
	v_pk_fma_f32 v[216:217], v[44:45], v[108:109], v[216:217]
	v_pk_fma_f32 v[218:219], v[46:47], v[110:111], v[218:219]
	v_pk_fma_f32 v[220:221], v[48:49], v[112:113], v[220:221]
	v_mul_f32_e32 v230, v122, v122
	v_mul_f32_e32 v231, v123, v123
	v_mul_f32_e32 v232, v124, v124
	v_mul_f32_e32 v233, v125, v125
	v_mul_f32_e32 v234, v126, v126
	v_mul_f32_e32 v235, v127, v127
	v_mul_f32_e32 v236, v128, v128
	v_mul_f32_e32 v237, v129, v129
	v_fma_f32 v230, v230, s22, v198
	v_fma_f32 v231, v231, s22, v198
	v_fma_f32 v232, v232, s22, v198
	v_fma_f32 v233, v233, s22, v198
	v_fma_f32 v234, v234, s22, v198
	v_fma_f32 v235, v235, s22, v198
	v_fma_f32 v236, v236, s22, v198
	v_fma_f32 v237, v237, s22, v198
	v_mul_f32_e32 v230, v122, v230
	v_mul_f32_e32 v231, v123, v231
	v_mul_f32_e32 v232, v124, v232
	v_mul_f32_e32 v233, v125, v233
	v_mul_f32_e32 v234, v126, v234
	v_mul_f32_e32 v235, v127, v235
	v_mul_f32_e32 v236, v128, v236
	v_mul_f32_e32 v237, v129, v237
	v_exp_f32_e32 v230, v230
	v_exp_f32_e32 v231, v231
	v_exp_f32_e32 v232, v232
	v_exp_f32_e32 v233, v233
	v_exp_f32_e32 v234, v234
	v_exp_f32_e32 v235, v235
	v_exp_f32_e32 v236, v236
	v_exp_f32_e32 v237, v237
	v_add_f32_e32 v230, 1.0, v230
	v_add_f32_e32 v231, 1.0, v231
	v_add_f32_e32 v232, 1.0, v232
	v_add_f32_e32 v233, 1.0, v233
	v_add_f32_e32 v234, 1.0, v234
	v_add_f32_e32 v235, 1.0, v235
	v_add_f32_e32 v236, 1.0, v236
	v_add_f32_e32 v237, 1.0, v237
	v_rcp_f32_e32 v230, v230
	v_rcp_f32_e32 v231, v231
	v_rcp_f32_e32 v232, v232
	v_rcp_f32_e32 v233, v233
	v_rcp_f32_e32 v234, v234
	v_rcp_f32_e32 v235, v235
	v_rcp_f32_e32 v236, v236
	v_rcp_f32_e32 v237, v237
	v_mul_f32_e32 v230, v122, v230
	v_mul_f32_e32 v231, v123, v231
	v_mul_f32_e32 v232, v124, v232
	v_mul_f32_e32 v233, v125, v233
	v_mul_f32_e32 v234, v126, v234
	v_mul_f32_e32 v235, v127, v235
	v_mul_f32_e32 v236, v128, v236
	v_mul_f32_e32 v237, v129, v237
	v_mul_f32_e32 v230, v230, v214
	v_mul_f32_e32 v231, v231, v215
	v_mul_f32_e32 v232, v232, v216
	v_mul_f32_e32 v233, v233, v217
	v_mul_f32_e32 v234, v234, v218
	v_mul_f32_e32 v235, v235, v219
	v_mul_f32_e32 v236, v236, v220
	v_mul_f32_e32 v237, v237, v221
	v_cvt_pk_bf16_f32 v240, v230, v231
	v_cvt_pk_bf16_f32 v241, v232, v233
	v_cvt_pk_bf16_f32 v242, v234, v235
	v_cvt_pk_bf16_f32 v243, v236, v237
	s_and_saveexec_b64 s[96:97], s[58:59]
	global_store_dwordx4 v144, v[240:243], s[2:3]
	s_mov_b64 exec, s[96:97]
	v_add_u32_e32 v144, 0x1600, v144
	s_waitcnt lgkmcnt(2)
	v_lshlrev_b32_e32 v66, 16, v222
	v_and_b32_e32 v67, s21, v222
	v_lshlrev_b32_e32 v68, 16, v223
	v_and_b32_e32 v69, s21, v223
	v_lshlrev_b32_e32 v70, 16, v224
	v_and_b32_e32 v71, s21, v224
	v_lshlrev_b32_e32 v72, 16, v225
	v_and_b32_e32 v73, s21, v225
	v_lshlrev_b32_e32 v74, 16, v226
	v_and_b32_e32 v75, s21, v226
	v_lshlrev_b32_e32 v76, 16, v227
	v_and_b32_e32 v77, s21, v227
	v_lshlrev_b32_e32 v78, 16, v228
	v_and_b32_e32 v79, s21, v228
	v_lshlrev_b32_e32 v80, 16, v229
	v_and_b32_e32 v81, s21, v229
	v_add_u32_e32 v145, 3, v142
	v_and_b32_e32 v146, 31, v145
	v_xor_b32_e32 v146, v146, v140
	v_lshlrev_b32_e32 v146, 4, v146
	v_lshl_or_b32 v146, v145, 9, v146
	v_xor_b32_e32 v147, 0x100, v146
	ds_read_b128 v[222:225], v146
	ds_read_b128 v[226:229], v147
	v_pk_fma_f32 v[122:123], v[2:3], v[82:83], v[50:51]
	v_pk_fma_f32 v[124:125], v[4:5], v[84:85], v[52:53]
	v_pk_fma_f32 v[126:127], v[6:7], v[86:87], v[54:55]
	v_pk_fma_f32 v[128:129], v[8:9], v[88:89], v[56:57]
	v_pk_fma_f32 v[214:215], v[10:11], v[90:91], v[58:59]
	v_pk_fma_f32 v[216:217], v[12:13], v[92:93], v[60:61]
	v_pk_fma_f32 v[218:219], v[14:15], v[94:95], v[62:63]
	v_pk_fma_f32 v[220:221], v[16:17], v[96:97], v[64:65]
	v_pk_fma_f32 v[122:123], v[18:19], v[98:99], v[122:123]
	v_pk_fma_f32 v[124:125], v[20:21], v[100:101], v[124:125]
	v_pk_fma_f32 v[126:127], v[22:23], v[102:103], v[126:127]
	v_pk_fma_f32 v[128:129], v[24:25], v[104:105], v[128:129]
	v_pk_fma_f32 v[214:215], v[26:27], v[106:107], v[214:215]
	v_pk_fma_f32 v[216:217], v[28:29], v[108:109], v[216:217]
	v_pk_fma_f32 v[218:219], v[30:31], v[110:111], v[218:219]
	v_pk_fma_f32 v[220:221], v[32:33], v[112:113], v[220:221]
	v_pk_fma_f32 v[122:123], v[34:35], v[66:67], v[122:123]
	v_pk_fma_f32 v[124:125], v[36:37], v[68:69], v[124:125]
	v_pk_fma_f32 v[126:127], v[38:39], v[70:71], v[126:127]
	v_pk_fma_f32 v[128:129], v[40:41], v[72:73], v[128:129]
	v_pk_fma_f32 v[214:215], v[42:43], v[74:75], v[214:215]
	v_pk_fma_f32 v[216:217], v[44:45], v[76:77], v[216:217]
; #define GAS __attribute__((address_space(1)))
;     ...
;           for (int h = 0; h < 2; ++h) {
;             const int c16 = h * 16 + ck;
;             float cur[8], p1[8], p2[8];
;             ld8(reinterpret_cast<const u16*>(st + row * 512 + ((c16 ^ (row & 31)) << 4)), cur);
;             if (t >= 1) ld8(reinterpret_cast<const u16*>(st + (row - 1) * 512 + ((c16 ^ ((row - 1) & 31)) << 4)), p1);
;             else if (samp) ld8f(p->cstate + ((size_t)b * 2 + 1) * UPW + ch + h * DFF, p1);
;             else { for (int k = 0; k < 8; ++k) p1[k] = 0.f; }
;             if (t >= 2) ld8(reinterpret_cast<const u16*>(st + (row - 2) * 512 + ((c16 ^ ((row - 2) & 31)) << 4)), p2);
;             else if (samp) ld8f(p->cstate + ((size_t)b * 2 + t) * UPW + ch + h * DFF, p2);
;             else { for (int k = 0; k < 8; ++k) p2[k] = 0.f; }
; #pragma unroll
;             for (int k = 0; k < 8; ++k) {
;               float cv = bb[h][k] + w0[h][k] * p2[k] + w1[h][k] * p1[k] + w2[h][k] * cur[k];
;               if (h == 0) res[k] = gelu_f(cv); else res[k] *= cv;
;             }
;           }
;           *(GAS uint4*)(FI + (size_t)(cur_brow + row) * DFF + ch) =
;               make_uint4(pack2(res[0], res[1]), pack2(res[2], res[3]), pack2(res[4], res[5]), pack2(res[6], res[7]));
	v_pk_fma_f32 v[218:219], v[46:47], v[78:79], v[218:219]
	v_pk_fma_f32 v[220:221], v[48:49], v[80:81], v[220:221]
	v_mul_f32_e32 v230, v122, v122
	v_mul_f32_e32 v231, v123, v123
	v_mul_f32_e32 v232, v124, v124
	v_mul_f32_e32 v233, v125, v125
	v_mul_f32_e32 v234, v126, v126
	v_mul_f32_e32 v235, v127, v127
	v_mul_f32_e32 v236, v128, v128
	v_mul_f32_e32 v237, v129, v129
	v_fma_f32 v230, v230, s22, v198
	v_fma_f32 v231, v231, s22, v198
	v_fma_f32 v232, v232, s22, v198
	v_fma_f32 v233, v233, s22, v198
	v_fma_f32 v234, v234, s22, v198
	v_fma_f32 v235, v235, s22, v198
	v_fma_f32 v236, v236, s22, v198
	v_fma_f32 v237, v237, s22, v198
	v_mul_f32_e32 v230, v122, v230
	v_mul_f32_e32 v231, v123, v231
	v_mul_f32_e32 v232, v124, v232
	v_mul_f32_e32 v233, v125, v233
	v_mul_f32_e32 v234, v126, v234
	v_mul_f32_e32 v235, v127, v235
	v_mul_f32_e32 v236, v128, v236
	v_mul_f32_e32 v237, v129, v237
	v_exp_f32_e32 v230, v230
	v_exp_f32_e32 v231, v231
	v_exp_f32_e32 v232, v232
	v_exp_f32_e32 v233, v233
	v_exp_f32_e32 v234, v234
	v_exp_f32_e32 v235, v235
	v_exp_f32_e32 v236, v236
	v_exp_f32_e32 v237, v237
	v_add_f32_e32 v230, 1.0, v230
	v_add_f32_e32 v231, 1.0, v231
	v_add_f32_e32 v232, 1.0, v232
	v_add_f32_e32 v233, 1.0, v233
	v_add_f32_e32 v234, 1.0, v234
	v_add_f32_e32 v235, 1.0, v235
	v_add_f32_e32 v236, 1.0, v236
	v_add_f32_e32 v237, 1.0, v237
	v_rcp_f32_e32 v230, v230
	v_rcp_f32_e32 v231, v231
	v_rcp_f32_e32 v232, v232
	v_rcp_f32_e32 v233, v233
	v_rcp_f32_e32 v234, v234
	v_rcp_f32_e32 v235, v235
	v_rcp_f32_e32 v236, v236
	v_rcp_f32_e32 v237, v237
	v_mul_f32_e32 v230, v122, v230
	v_mul_f32_e32 v231, v123, v231
	v_mul_f32_e32 v232, v124, v232
	v_mul_f32_e32 v233, v125, v233
	v_mul_f32_e32 v234, v126, v234
	v_mul_f32_e32 v235, v127, v235
	v_mul_f32_e32 v236, v128, v236
	v_mul_f32_e32 v237, v129, v237
	v_mul_f32_e32 v230, v230, v214
	v_mul_f32_e32 v231, v231, v215
	v_mul_f32_e32 v232, v232, v216
	v_mul_f32_e32 v233, v233, v217
	v_mul_f32_e32 v234, v234, v218
	v_mul_f32_e32 v235, v235, v219
	v_mul_f32_e32 v236, v236, v220
	v_mul_f32_e32 v237, v237, v221
	v_cvt_pk_bf16_f32 v240, v230, v231
	v_cvt_pk_bf16_f32 v241, v232, v233
	v_cvt_pk_bf16_f32 v242, v234, v235
	v_cvt_pk_bf16_f32 v243, v236, v237
	s_and_saveexec_b64 s[96:97], s[58:59]
	global_store_dwordx4 v144, v[240:243], s[2:3]
	s_mov_b64 exec, s[96:97]
	v_add_u32_e32 v144, 0x1600, v144
	s_waitcnt lgkmcnt(2)
	v_lshlrev_b32_e32 v82, 16, v114
	v_and_b32_e32 v83, s21, v114
	v_lshlrev_b32_e32 v84, 16, v115
	v_and_b32_e32 v85, s21, v115
	v_lshlrev_b32_e32 v86, 16, v116
	v_and_b32_e32 v87, s21, v116
	v_lshlrev_b32_e32 v88, 16, v117
	v_and_b32_e32 v89, s21, v117
	v_lshlrev_b32_e32 v90, 16, v118
	v_and_b32_e32 v91, s21, v118
	v_lshlrev_b32_e32 v92, 16, v119
	v_and_b32_e32 v93, s21, v119
	v_lshlrev_b32_e32 v94, 16, v120
	v_and_b32_e32 v95, s21, v120
	v_lshlrev_b32_e32 v96, 16, v121
	v_and_b32_e32 v97, s21, v121
	v_add_u32_e32 v145, 4, v142
	v_and_b32_e32 v146, 31, v145
	v_xor_b32_e32 v146, v146, v140
	v_lshlrev_b32_e32 v146, 4, v146
	v_lshl_or_b32 v146, v145, 9, v146
	v_xor_b32_e32 v147, 0x100, v146
	ds_read_b128 v[114:117], v146
	ds_read_b128 v[118:121], v147
	v_pk_fma_f32 v[122:123], v[2:3], v[98:99], v[50:51]
	v_pk_fma_f32 v[124:125], v[4:5], v[100:101], v[52:53]
	v_pk_fma_f32 v[126:127], v[6:7], v[102:103], v[54:55]
	v_pk_fma_f32 v[128:129], v[8:9], v[104:105], v[56:57]
	v_pk_fma_f32 v[214:215], v[10:11], v[106:107], v[58:59]
	v_pk_fma_f32 v[216:217], v[12:13], v[108:109], v[60:61]
	v_pk_fma_f32 v[218:219], v[14:15], v[110:111], v[62:63]
	v_pk_fma_f32 v[220:221], v[16:17], v[112:113], v[64:65]
	v_pk_fma_f32 v[122:123], v[18:19], v[66:67], v[122:123]
	v_pk_fma_f32 v[124:125], v[20:21], v[68:69], v[124:125]
	v_pk_fma_f32 v[126:127], v[22:23], v[70:71], v[126:127]
	v_pk_fma_f32 v[128:129], v[24:25], v[72:73], v[128:129]
	v_pk_fma_f32 v[214:215], v[26:27], v[74:75], v[214:215]
	v_pk_fma_f32 v[216:217], v[28:29], v[76:77], v[216:217]
	v_pk_fma_f32 v[218:219], v[30:31], v[78:79], v[218:219]
	v_pk_fma_f32 v[220:221], v[32:33], v[80:81], v[220:221]
	v_pk_fma_f32 v[122:123], v[34:35], v[82:83], v[122:123]
	v_pk_fma_f32 v[124:125], v[36:37], v[84:85], v[124:125]
	v_pk_fma_f32 v[126:127], v[38:39], v[86:87], v[126:127]
	v_pk_fma_f32 v[128:129], v[40:41], v[88:89], v[128:129]
	v_pk_fma_f32 v[214:215], v[42:43], v[90:91], v[214:215]
	v_pk_fma_f32 v[216:217], v[44:45], v[92:93], v[216:217]
	v_pk_fma_f32 v[218:219], v[46:47], v[94:95], v[218:219]
	v_pk_fma_f32 v[220:221], v[48:49], v[96:97], v[220:221]
	v_mul_f32_e32 v230, v122, v122
	v_mul_f32_e32 v231, v123, v123
	v_mul_f32_e32 v232, v124, v124
	v_mul_f32_e32 v233, v125, v125
	v_mul_f32_e32 v234, v126, v126
	v_mul_f32_e32 v235, v127, v127
	v_mul_f32_e32 v236, v128, v128
	v_mul_f32_e32 v237, v129, v129
	v_fma_f32 v230, v230, s22, v198
	v_fma_f32 v231, v231, s22, v198
	v_fma_f32 v232, v232, s22, v198
	v_fma_f32 v233, v233, s22, v198
	v_fma_f32 v234, v234, s22, v198
	v_fma_f32 v235, v235, s22, v198
	v_fma_f32 v236, v236, s22, v198
	v_fma_f32 v237, v237, s22, v198
	v_mul_f32_e32 v230, v122, v230
	v_mul_f32_e32 v231, v123, v231
	v_mul_f32_e32 v232, v124, v232
	v_mul_f32_e32 v233, v125, v233
	v_mul_f32_e32 v234, v126, v234
	v_mul_f32_e32 v235, v127, v235
	v_mul_f32_e32 v236, v128, v236
	v_mul_f32_e32 v237, v129, v237
	v_exp_f32_e32 v230, v230
	v_exp_f32_e32 v231, v231
	v_exp_f32_e32 v232, v232
	v_exp_f32_e32 v233, v233
	v_exp_f32_e32 v234, v234
	v_exp_f32_e32 v235, v235
	v_exp_f32_e32 v236, v236
	v_exp_f32_e32 v237, v237
	v_add_f32_e32 v230, 1.0, v230
	v_add_f32_e32 v231, 1.0, v231
	v_add_f32_e32 v232, 1.0, v232
	v_add_f32_e32 v233, 1.0, v233
	v_add_f32_e32 v234, 1.0, v234
	v_add_f32_e32 v235, 1.0, v235
	v_add_f32_e32 v236, 1.0, v236
	v_add_f32_e32 v237, 1.0, v237
	v_rcp_f32_e32 v230, v230
	v_rcp_f32_e32 v231, v231
	v_rcp_f32_e32 v232, v232
	v_rcp_f32_e32 v233, v233
	v_rcp_f32_e32 v234, v234
	v_rcp_f32_e32 v235, v235
	v_rcp_f32_e32 v236, v236
	v_rcp_f32_e32 v237, v237
	v_mul_f32_e32 v230, v122, v230
	v_mul_f32_e32 v231, v123, v231
	v_mul_f32_e32 v232, v124, v232
	v_mul_f32_e32 v233, v125, v233
	v_mul_f32_e32 v234, v126, v234
	v_mul_f32_e32 v235, v127, v235
	v_mul_f32_e32 v236, v128, v236
	v_mul_f32_e32 v237, v129, v237
	v_mul_f32_e32 v230, v230, v214
	v_mul_f32_e32 v231, v231, v215
	v_mul_f32_e32 v232, v232, v216
	v_mul_f32_e32 v233, v233, v217
	v_mul_f32_e32 v234, v234, v218
	v_mul_f32_e32 v235, v235, v219
	v_mul_f32_e32 v236, v236, v220
	v_mul_f32_e32 v237, v237, v221
	v_cvt_pk_bf16_f32 v240, v230, v231
	v_cvt_pk_bf16_f32 v241, v232, v233
	v_cvt_pk_bf16_f32 v242, v234, v235
	v_cvt_pk_bf16_f32 v243, v236, v237
	global_store_dwordx4 v144, v[240:243], s[2:3]
	v_add_u32_e32 v144, 0x1600, v144
	s_waitcnt lgkmcnt(2)
; #define GAS __attribute__((address_space(1)))
;     ...
;           for (int h = 0; h < 2; ++h) {
;             const int c16 = h * 16 + ck;
;             float cur[8], p1[8], p2[8];
;             ld8(reinterpret_cast<const u16*>(st + row * 512 + ((c16 ^ (row & 31)) << 4)), cur);
;             if (t >= 1) ld8(reinterpret_cast<const u16*>(st + (row - 1) * 512 + ((c16 ^ ((row - 1) & 31)) << 4)), p1);
;             else if (samp) ld8f(p->cstate + ((size_t)b * 2 + 1) * UPW + ch + h * DFF, p1);
;             else { for (int k = 0; k < 8; ++k) p1[k] = 0.f; }
;             if (t >= 2) ld8(reinterpret_cast<const u16*>(st + (row - 2) * 512 + ((c16 ^ ((row - 2) & 31)) << 4)), p2);
;             else if (samp) ld8f(p->cstate + ((size_t)b * 2 + t) * UPW + ch + h * DFF, p2);
;             else { for (int k = 0; k < 8; ++k) p2[k] = 0.f; }
; #pragma unroll
;             for (int k = 0; k < 8; ++k) {
;               float cv = bb[h][k] + w0[h][k] * p2[k] + w1[h][k] * p1[k] + w2[h][k] * cur[k];
;               if (h == 0) res[k] = gelu_f(cv); else res[k] *= cv;
;             }
;           }
;           *(GAS uint4*)(FI + (size_t)(cur_brow + row) * DFF + ch) =
;               make_uint4(pack2(res[0], res[1]), pack2(res[2], res[3]), pack2(res[4], res[5]), pack2(res[6], res[7]));
	v_lshlrev_b32_e32 v98, 16, v222
	v_and_b32_e32 v99, s21, v222
	v_lshlrev_b32_e32 v100, 16, v223
	v_and_b32_e32 v101, s21, v223
	v_lshlrev_b32_e32 v102, 16, v224
	v_and_b32_e32 v103, s21, v224
	v_lshlrev_b32_e32 v104, 16, v225
	v_and_b32_e32 v105, s21, v225
	v_lshlrev_b32_e32 v106, 16, v226
	v_and_b32_e32 v107, s21, v226
	v_lshlrev_b32_e32 v108, 16, v227
	v_and_b32_e32 v109, s21, v227
	v_lshlrev_b32_e32 v110, 16, v228
	v_and_b32_e32 v111, s21, v228
	v_lshlrev_b32_e32 v112, 16, v229
	v_and_b32_e32 v113, s21, v229
	v_add_u32_e32 v145, 5, v142
	v_and_b32_e32 v146, 31, v145
	v_xor_b32_e32 v146, v146, v140
	v_lshlrev_b32_e32 v146, 4, v146
	v_lshl_or_b32 v146, v145, 9, v146
	v_xor_b32_e32 v147, 0x100, v146
	ds_read_b128 v[222:225], v146
	ds_read_b128 v[226:229], v147
	v_pk_fma_f32 v[122:123], v[2:3], v[66:67], v[50:51]
	v_pk_fma_f32 v[124:125], v[4:5], v[68:69], v[52:53]
	v_pk_fma_f32 v[126:127], v[6:7], v[70:71], v[54:55]
	v_pk_fma_f32 v[128:129], v[8:9], v[72:73], v[56:57]
	v_pk_fma_f32 v[214:215], v[10:11], v[74:75], v[58:59]
	v_pk_fma_f32 v[216:217], v[12:13], v[76:77], v[60:61]
	v_pk_fma_f32 v[218:219], v[14:15], v[78:79], v[62:63]
	v_pk_fma_f32 v[220:221], v[16:17], v[80:81], v[64:65]
	v_pk_fma_f32 v[122:123], v[18:19], v[82:83], v[122:123]
	v_pk_fma_f32 v[124:125], v[20:21], v[84:85], v[124:125]
	v_pk_fma_f32 v[126:127], v[22:23], v[86:87], v[126:127]
	v_pk_fma_f32 v[128:129], v[24:25], v[88:89], v[128:129]
	v_pk_fma_f32 v[214:215], v[26:27], v[90:91], v[214:215]
	v_pk_fma_f32 v[216:217], v[28:29], v[92:93], v[216:217]
	v_pk_fma_f32 v[218:219], v[30:31], v[94:95], v[218:219]
	v_pk_fma_f32 v[220:221], v[32:33], v[96:97], v[220:221]
	v_pk_fma_f32 v[122:123], v[34:35], v[98:99], v[122:123]
	v_pk_fma_f32 v[124:125], v[36:37], v[100:101], v[124:125]
	v_pk_fma_f32 v[126:127], v[38:39], v[102:103], v[126:127]
	v_pk_fma_f32 v[128:129], v[40:41], v[104:105], v[128:129]
	v_pk_fma_f32 v[214:215], v[42:43], v[106:107], v[214:215]
	v_pk_fma_f32 v[216:217], v[44:45], v[108:109], v[216:217]
	v_pk_fma_f32 v[218:219], v[46:47], v[110:111], v[218:219]
	v_pk_fma_f32 v[220:221], v[48:49], v[112:113], v[220:221]
	v_mul_f32_e32 v230, v122, v122
	v_mul_f32_e32 v231, v123, v123
	v_mul_f32_e32 v232, v124, v124
	v_mul_f32_e32 v233, v125, v125
	v_mul_f32_e32 v234, v126, v126
	v_mul_f32_e32 v235, v127, v127
	v_mul_f32_e32 v236, v128, v128
	v_mul_f32_e32 v237, v129, v129
	v_fma_f32 v230, v230, s22, v198
	v_fma_f32 v231, v231, s22, v198
	v_fma_f32 v232, v232, s22, v198
	v_fma_f32 v233, v233, s22, v198
	v_fma_f32 v234, v234, s22, v198
	v_fma_f32 v235, v235, s22, v198
	v_fma_f32 v236, v236, s22, v198
	v_fma_f32 v237, v237, s22, v198
	v_mul_f32_e32 v230, v122, v230
	v_mul_f32_e32 v231, v123, v231
	v_mul_f32_e32 v232, v124, v232
	v_mul_f32_e32 v233, v125, v233
	v_mul_f32_e32 v234, v126, v234
	v_mul_f32_e32 v235, v127, v235
	v_mul_f32_e32 v236, v128, v236
	v_mul_f32_e32 v237, v129, v237
	v_exp_f32_e32 v230, v230
	v_exp_f32_e32 v231, v231
	v_exp_f32_e32 v232, v232
	v_exp_f32_e32 v233, v233
	v_exp_f32_e32 v234, v234
	v_exp_f32_e32 v235, v235
	v_exp_f32_e32 v236, v236
	v_exp_f32_e32 v237, v237
	v_add_f32_e32 v230, 1.0, v230
	v_add_f32_e32 v231, 1.0, v231
	v_add_f32_e32 v232, 1.0, v232
	v_add_f32_e32 v233, 1.0, v233
	v_add_f32_e32 v234, 1.0, v234
	v_add_f32_e32 v235, 1.0, v235
	v_add_f32_e32 v236, 1.0, v236
	v_add_f32_e32 v237, 1.0, v237
	v_rcp_f32_e32 v230, v230
	v_rcp_f32_e32 v231, v231
	v_rcp_f32_e32 v232, v232
	v_rcp_f32_e32 v233, v233
	v_rcp_f32_e32 v234, v234
	v_rcp_f32_e32 v235, v235
	v_rcp_f32_e32 v236, v236
	v_rcp_f32_e32 v237, v237
	v_mul_f32_e32 v230, v122, v230
	v_mul_f32_e32 v231, v123, v231
	v_mul_f32_e32 v232, v124, v232
	v_mul_f32_e32 v233, v125, v233
	v_mul_f32_e32 v234, v126, v234
	v_mul_f32_e32 v235, v127, v235
	v_mul_f32_e32 v236, v128, v236
	v_mul_f32_e32 v237, v129, v237
	v_mul_f32_e32 v230, v230, v214
	v_mul_f32_e32 v231, v231, v215
	v_mul_f32_e32 v232, v232, v216
	v_mul_f32_e32 v233, v233, v217
	v_mul_f32_e32 v234, v234, v218
	v_mul_f32_e32 v235, v235, v219
	v_mul_f32_e32 v236, v236, v220
	v_mul_f32_e32 v237, v237, v221
	v_cvt_pk_bf16_f32 v240, v230, v231
	v_cvt_pk_bf16_f32 v241, v232, v233
	v_cvt_pk_bf16_f32 v242, v234, v235
	v_cvt_pk_bf16_f32 v243, v236, v237
	global_store_dwordx4 v144, v[240:243], s[2:3]
	v_add_u32_e32 v144, 0x1600, v144
	s_waitcnt lgkmcnt(2)
; #define GAS __attribute__((address_space(1)))
;     ...
;           for (int h = 0; h < 2; ++h) {
;             const int c16 = h * 16 + ck;
;             float cur[8], p1[8], p2[8];
;             ld8(reinterpret_cast<const u16*>(st + row * 512 + ((c16 ^ (row & 31)) << 4)), cur);
;             if (t >= 1) ld8(reinterpret_cast<const u16*>(st + (row - 1) * 512 + ((c16 ^ ((row - 1) & 31)) << 4)), p1);
;             else if (samp) ld8f(p->cstate + ((size_t)b * 2 + 1) * UPW + ch + h * DFF, p1);
;             else { for (int k = 0; k < 8; ++k) p1[k] = 0.f; }
;             if (t >= 2) ld8(reinterpret_cast<const u16*>(st + (row - 2) * 512 + ((c16 ^ ((row - 2) & 31)) << 4)), p2);
;             else if (samp) ld8f(p->cstate + ((size_t)b * 2 + t) * UPW + ch + h * DFF, p2);
;             else { for (int k = 0; k < 8; ++k) p2[k] = 0.f; }
; #pragma unroll
;             for (int k = 0; k < 8; ++k) {
;               float cv = bb[h][k] + w0[h][k] * p2[k] + w1[h][k] * p1[k] + w2[h][k] * cur[k];
;               if (h == 0) res[k] = gelu_f(cv); else res[k] *= cv;
;             }
;           }
;           *(GAS uint4*)(FI + (size_t)(cur_brow + row) * DFF + ch) =
;               make_uint4(pack2(res[0], res[1]), pack2(res[2], res[3]), pack2(res[4], res[5]), pack2(res[6], res[7]));
	v_lshlrev_b32_e32 v66, 16, v114
	v_and_b32_e32 v67, s21, v114
	v_lshlrev_b32_e32 v68, 16, v115
	v_and_b32_e32 v69, s21, v115
	v_lshlrev_b32_e32 v70, 16, v116
	v_and_b32_e32 v71, s21, v116
	v_lshlrev_b32_e32 v72, 16, v117
	v_and_b32_e32 v73, s21, v117
	v_lshlrev_b32_e32 v74, 16, v118
	v_and_b32_e32 v75, s21, v118
	v_lshlrev_b32_e32 v76, 16, v119
	v_and_b32_e32 v77, s21, v119
	v_lshlrev_b32_e32 v78, 16, v120
	v_and_b32_e32 v79, s21, v120
	v_lshlrev_b32_e32 v80, 16, v121
	v_and_b32_e32 v81, s21, v121
	v_add_u32_e32 v145, 6, v142
	v_and_b32_e32 v146, 31, v145
	v_xor_b32_e32 v146, v146, v140
	v_lshlrev_b32_e32 v146, 4, v146
	v_lshl_or_b32 v146, v145, 9, v146
	v_xor_b32_e32 v147, 0x100, v146
	ds_read_b128 v[114:117], v146
	ds_read_b128 v[118:121], v147
	v_pk_fma_f32 v[122:123], v[2:3], v[82:83], v[50:51]
	v_pk_fma_f32 v[124:125], v[4:5], v[84:85], v[52:53]
	v_pk_fma_f32 v[126:127], v[6:7], v[86:87], v[54:55]
	v_pk_fma_f32 v[128:129], v[8:9], v[88:89], v[56:57]
	v_pk_fma_f32 v[214:215], v[10:11], v[90:91], v[58:59]
	v_pk_fma_f32 v[216:217], v[12:13], v[92:93], v[60:61]
	v_pk_fma_f32 v[218:219], v[14:15], v[94:95], v[62:63]
	v_pk_fma_f32 v[220:221], v[16:17], v[96:97], v[64:65]
	v_pk_fma_f32 v[122:123], v[18:19], v[98:99], v[122:123]
	v_pk_fma_f32 v[124:125], v[20:21], v[100:101], v[124:125]
	v_pk_fma_f32 v[126:127], v[22:23], v[102:103], v[126:127]
	v_pk_fma_f32 v[128:129], v[24:25], v[104:105], v[128:129]
	v_pk_fma_f32 v[214:215], v[26:27], v[106:107], v[214:215]
	v_pk_fma_f32 v[216:217], v[28:29], v[108:109], v[216:217]
	v_pk_fma_f32 v[218:219], v[30:31], v[110:111], v[218:219]
	v_pk_fma_f32 v[220:221], v[32:33], v[112:113], v[220:221]
	v_pk_fma_f32 v[122:123], v[34:35], v[66:67], v[122:123]
	v_pk_fma_f32 v[124:125], v[36:37], v[68:69], v[124:125]
	v_pk_fma_f32 v[126:127], v[38:39], v[70:71], v[126:127]
	v_pk_fma_f32 v[128:129], v[40:41], v[72:73], v[128:129]
	v_pk_fma_f32 v[214:215], v[42:43], v[74:75], v[214:215]
	v_pk_fma_f32 v[216:217], v[44:45], v[76:77], v[216:217]
	v_pk_fma_f32 v[218:219], v[46:47], v[78:79], v[218:219]
	v_pk_fma_f32 v[220:221], v[48:49], v[80:81], v[220:221]
	v_mul_f32_e32 v230, v122, v122
	v_mul_f32_e32 v231, v123, v123
	v_mul_f32_e32 v232, v124, v124
	v_mul_f32_e32 v233, v125, v125
	v_mul_f32_e32 v234, v126, v126
	v_mul_f32_e32 v235, v127, v127
	v_mul_f32_e32 v236, v128, v128
	v_mul_f32_e32 v237, v129, v129
	v_fma_f32 v230, v230, s22, v198
	v_fma_f32 v231, v231, s22, v198
	v_fma_f32 v232, v232, s22, v198
	v_fma_f32 v233, v233, s22, v198
	v_fma_f32 v234, v234, s22, v198
	v_fma_f32 v235, v235, s22, v198
	v_fma_f32 v236, v236, s22, v198
	v_fma_f32 v237, v237, s22, v198
	v_mul_f32_e32 v230, v122, v230
	v_mul_f32_e32 v231, v123, v231
	v_mul_f32_e32 v232, v124, v232
	v_mul_f32_e32 v233, v125, v233
	v_mul_f32_e32 v234, v126, v234
	v_mul_f32_e32 v235, v127, v235
	v_mul_f32_e32 v236, v128, v236
	v_mul_f32_e32 v237, v129, v237
	v_exp_f32_e32 v230, v230
	v_exp_f32_e32 v231, v231
	v_exp_f32_e32 v232, v232
	v_exp_f32_e32 v233, v233
	v_exp_f32_e32 v234, v234
	v_exp_f32_e32 v235, v235
	v_exp_f32_e32 v236, v236
	v_exp_f32_e32 v237, v237
	v_add_f32_e32 v230, 1.0, v230
	v_add_f32_e32 v231, 1.0, v231
	v_add_f32_e32 v232, 1.0, v232
	v_add_f32_e32 v233, 1.0, v233
	v_add_f32_e32 v234, 1.0, v234
	v_add_f32_e32 v235, 1.0, v235
	v_add_f32_e32 v236, 1.0, v236
	v_add_f32_e32 v237, 1.0, v237
	v_rcp_f32_e32 v230, v230
	v_rcp_f32_e32 v231, v231
	v_rcp_f32_e32 v232, v232
	v_rcp_f32_e32 v233, v233
	v_rcp_f32_e32 v234, v234
	v_rcp_f32_e32 v235, v235
	v_rcp_f32_e32 v236, v236
	v_rcp_f32_e32 v237, v237
	v_mul_f32_e32 v230, v122, v230
	v_mul_f32_e32 v231, v123, v231
	v_mul_f32_e32 v232, v124, v232
	v_mul_f32_e32 v233, v125, v233
	v_mul_f32_e32 v234, v126, v234
	v_mul_f32_e32 v235, v127, v235
	v_mul_f32_e32 v236, v128, v236
	v_mul_f32_e32 v237, v129, v237
	v_mul_f32_e32 v230, v230, v214
	v_mul_f32_e32 v231, v231, v215
	v_mul_f32_e32 v232, v232, v216
	v_mul_f32_e32 v233, v233, v217
	v_mul_f32_e32 v234, v234, v218
	v_mul_f32_e32 v235, v235, v219
	v_mul_f32_e32 v236, v236, v220
	v_mul_f32_e32 v237, v237, v221
	v_cvt_pk_bf16_f32 v240, v230, v231
	v_cvt_pk_bf16_f32 v241, v232, v233
	v_cvt_pk_bf16_f32 v242, v234, v235
	v_cvt_pk_bf16_f32 v243, v236, v237
	global_store_dwordx4 v144, v[240:243], s[2:3]
	v_add_u32_e32 v144, 0x1600, v144
	s_waitcnt lgkmcnt(2)
; #define GAS __attribute__((address_space(1)))
;     ...
;           for (int h = 0; h < 2; ++h) {
;             const int c16 = h * 16 + ck;
;             float cur[8], p1[8], p2[8];
;             ld8(reinterpret_cast<const u16*>(st + row * 512 + ((c16 ^ (row & 31)) << 4)), cur);
;             if (t >= 1) ld8(reinterpret_cast<const u16*>(st + (row - 1) * 512 + ((c16 ^ ((row - 1) & 31)) << 4)), p1);
;             else if (samp) ld8f(p->cstate + ((size_t)b * 2 + 1) * UPW + ch + h * DFF, p1);
;             else { for (int k = 0; k < 8; ++k) p1[k] = 0.f; }
;             if (t >= 2) ld8(reinterpret_cast<const u16*>(st + (row - 2) * 512 + ((c16 ^ ((row - 2) & 31)) << 4)), p2);
;             else if (samp) ld8f(p->cstate + ((size_t)b * 2 + t) * UPW + ch + h * DFF, p2);
;             else { for (int k = 0; k < 8; ++k) p2[k] = 0.f; }
; #pragma unroll
;             for (int k = 0; k < 8; ++k) {
;               float cv = bb[h][k] + w0[h][k] * p2[k] + w1[h][k] * p1[k] + w2[h][k] * cur[k];
;               if (h == 0) res[k] = gelu_f(cv); else res[k] *= cv;
;             }
;           }
;           *(GAS uint4*)(FI + (size_t)(cur_brow + row) * DFF + ch) =
;               make_uint4(pack2(res[0], res[1]), pack2(res[2], res[3]), pack2(res[4], res[5]), pack2(res[6], res[7]));
	v_lshlrev_b32_e32 v82, 16, v222
	v_and_b32_e32 v83, s21, v222
	v_lshlrev_b32_e32 v84, 16, v223
	v_and_b32_e32 v85, s21, v223
	v_lshlrev_b32_e32 v86, 16, v224
	v_and_b32_e32 v87, s21, v224
	v_lshlrev_b32_e32 v88, 16, v225
	v_and_b32_e32 v89, s21, v225
	v_lshlrev_b32_e32 v90, 16, v226
	v_and_b32_e32 v91, s21, v226
	v_lshlrev_b32_e32 v92, 16, v227
	v_and_b32_e32 v93, s21, v227
	v_lshlrev_b32_e32 v94, 16, v228
	v_and_b32_e32 v95, s21, v228
	v_lshlrev_b32_e32 v96, 16, v229
	v_and_b32_e32 v97, s21, v229
	v_add_u32_e32 v145, 7, v142
	v_and_b32_e32 v146, 31, v145
	v_xor_b32_e32 v146, v146, v140
	v_lshlrev_b32_e32 v146, 4, v146
	v_lshl_or_b32 v146, v145, 9, v146
	v_xor_b32_e32 v147, 0x100, v146
	ds_read_b128 v[222:225], v146
	ds_read_b128 v[226:229], v147
	v_pk_fma_f32 v[122:123], v[2:3], v[98:99], v[50:51]
	v_pk_fma_f32 v[124:125], v[4:5], v[100:101], v[52:53]
	v_pk_fma_f32 v[126:127], v[6:7], v[102:103], v[54:55]
	v_pk_fma_f32 v[128:129], v[8:9], v[104:105], v[56:57]
	v_pk_fma_f32 v[214:215], v[10:11], v[106:107], v[58:59]
	v_pk_fma_f32 v[216:217], v[12:13], v[108:109], v[60:61]
	v_pk_fma_f32 v[218:219], v[14:15], v[110:111], v[62:63]
	v_pk_fma_f32 v[220:221], v[16:17], v[112:113], v[64:65]
	v_pk_fma_f32 v[122:123], v[18:19], v[66:67], v[122:123]
	v_pk_fma_f32 v[124:125], v[20:21], v[68:69], v[124:125]
	v_pk_fma_f32 v[126:127], v[22:23], v[70:71], v[126:127]
	v_pk_fma_f32 v[128:129], v[24:25], v[72:73], v[128:129]
	v_pk_fma_f32 v[214:215], v[26:27], v[74:75], v[214:215]
	v_pk_fma_f32 v[216:217], v[28:29], v[76:77], v[216:217]
	v_pk_fma_f32 v[218:219], v[30:31], v[78:79], v[218:219]
	v_pk_fma_f32 v[220:221], v[32:33], v[80:81], v[220:221]
	v_pk_fma_f32 v[122:123], v[34:35], v[82:83], v[122:123]
	v_pk_fma_f32 v[124:125], v[36:37], v[84:85], v[124:125]
	v_pk_fma_f32 v[126:127], v[38:39], v[86:87], v[126:127]
	v_pk_fma_f32 v[128:129], v[40:41], v[88:89], v[128:129]
	v_pk_fma_f32 v[214:215], v[42:43], v[90:91], v[214:215]
	v_pk_fma_f32 v[216:217], v[44:45], v[92:93], v[216:217]
	v_pk_fma_f32 v[218:219], v[46:47], v[94:95], v[218:219]
	v_pk_fma_f32 v[220:221], v[48:49], v[96:97], v[220:221]
	v_mul_f32_e32 v230, v122, v122
	v_mul_f32_e32 v231, v123, v123
	v_mul_f32_e32 v232, v124, v124
	v_mul_f32_e32 v233, v125, v125
	v_mul_f32_e32 v234, v126, v126
	v_mul_f32_e32 v235, v127, v127
	v_mul_f32_e32 v236, v128, v128
	v_mul_f32_e32 v237, v129, v129
	v_fma_f32 v230, v230, s22, v198
	v_fma_f32 v231, v231, s22, v198
	v_fma_f32 v232, v232, s22, v198
	v_fma_f32 v233, v233, s22, v198
	v_fma_f32 v234, v234, s22, v198
	v_fma_f32 v235, v235, s22, v198
	v_fma_f32 v236, v236, s22, v198
	v_fma_f32 v237, v237, s22, v198
	v_mul_f32_e32 v230, v122, v230
	v_mul_f32_e32 v231, v123, v231
	v_mul_f32_e32 v232, v124, v232
	v_mul_f32_e32 v233, v125, v233
	v_mul_f32_e32 v234, v126, v234
	v_mul_f32_e32 v235, v127, v235
	v_mul_f32_e32 v236, v128, v236
	v_mul_f32_e32 v237, v129, v237
	v_exp_f32_e32 v230, v230
	v_exp_f32_e32 v231, v231
	v_exp_f32_e32 v232, v232
	v_exp_f32_e32 v233, v233
	v_exp_f32_e32 v234, v234
	v_exp_f32_e32 v235, v235
	v_exp_f32_e32 v236, v236
	v_exp_f32_e32 v237, v237
	v_add_f32_e32 v230, 1.0, v230
	v_add_f32_e32 v231, 1.0, v231
	v_add_f32_e32 v232, 1.0, v232
	v_add_f32_e32 v233, 1.0, v233
	v_add_f32_e32 v234, 1.0, v234
	v_add_f32_e32 v235, 1.0, v235
	v_add_f32_e32 v236, 1.0, v236
	v_add_f32_e32 v237, 1.0, v237
	v_rcp_f32_e32 v230, v230
	v_rcp_f32_e32 v231, v231
	v_rcp_f32_e32 v232, v232
	v_rcp_f32_e32 v233, v233
	v_rcp_f32_e32 v234, v234
	v_rcp_f32_e32 v235, v235
	v_rcp_f32_e32 v236, v236
	v_rcp_f32_e32 v237, v237
	v_mul_f32_e32 v230, v122, v230
	v_mul_f32_e32 v231, v123, v231
	v_mul_f32_e32 v232, v124, v232
	v_mul_f32_e32 v233, v125, v233
	v_mul_f32_e32 v234, v126, v234
	v_mul_f32_e32 v235, v127, v235
	v_mul_f32_e32 v236, v128, v236
	v_mul_f32_e32 v237, v129, v237
	v_mul_f32_e32 v230, v230, v214
	v_mul_f32_e32 v231, v231, v215
	v_mul_f32_e32 v232, v232, v216
	v_mul_f32_e32 v233, v233, v217
	v_mul_f32_e32 v234, v234, v218
	v_mul_f32_e32 v235, v235, v219
	v_mul_f32_e32 v236, v236, v220
	v_mul_f32_e32 v237, v237, v221
	v_cvt_pk_bf16_f32 v240, v230, v231
	v_cvt_pk_bf16_f32 v241, v232, v233
	v_cvt_pk_bf16_f32 v242, v234, v235
	v_cvt_pk_bf16_f32 v243, v236, v237
	global_store_dwordx4 v144, v[240:243], s[2:3]
	v_add_u32_e32 v144, 0x1600, v144
	s_waitcnt lgkmcnt(2)
; #define GAS __attribute__((address_space(1)))
;     ...
;           for (int h = 0; h < 2; ++h) {
;             const int c16 = h * 16 + ck;
;             float cur[8], p1[8], p2[8];
;             ld8(reinterpret_cast<const u16*>(st + row * 512 + ((c16 ^ (row & 31)) << 4)), cur);
;             if (t >= 1) ld8(reinterpret_cast<const u16*>(st + (row - 1) * 512 + ((c16 ^ ((row - 1) & 31)) << 4)), p1);
;             else if (samp) ld8f(p->cstate + ((size_t)b * 2 + 1) * UPW + ch + h * DFF, p1);
;             else { for (int k = 0; k < 8; ++k) p1[k] = 0.f; }
;             if (t >= 2) ld8(reinterpret_cast<const u16*>(st + (row - 2) * 512 + ((c16 ^ ((row - 2) & 31)) << 4)), p2);
;             else if (samp) ld8f(p->cstate + ((size_t)b * 2 + t) * UPW + ch + h * DFF, p2);
;             else { for (int k = 0; k < 8; ++k) p2[k] = 0.f; }
; #pragma unroll
;             for (int k = 0; k < 8; ++k) {
;               float cv = bb[h][k] + w0[h][k] * p2[k] + w1[h][k] * p1[k] + w2[h][k] * cur[k];
;               if (h == 0) res[k] = gelu_f(cv); else res[k] *= cv;
;             }
;           }
;           *(GAS uint4*)(FI + (size_t)(cur_brow + row) * DFF + ch) =
;               make_uint4(pack2(res[0], res[1]), pack2(res[2], res[3]), pack2(res[4], res[5]), pack2(res[6], res[7]));
	v_lshlrev_b32_e32 v98, 16, v114
	v_and_b32_e32 v99, s21, v114
	v_lshlrev_b32_e32 v100, 16, v115
	v_and_b32_e32 v101, s21, v115
	v_lshlrev_b32_e32 v102, 16, v116
	v_and_b32_e32 v103, s21, v116
	v_lshlrev_b32_e32 v104, 16, v117
	v_and_b32_e32 v105, s21, v117
	v_lshlrev_b32_e32 v106, 16, v118
	v_and_b32_e32 v107, s21, v118
	v_lshlrev_b32_e32 v108, 16, v119
	v_and_b32_e32 v109, s21, v119
	v_lshlrev_b32_e32 v110, 16, v120
	v_and_b32_e32 v111, s21, v120
	v_lshlrev_b32_e32 v112, 16, v121
	v_and_b32_e32 v113, s21, v121
	v_pk_fma_f32 v[122:123], v[2:3], v[66:67], v[50:51]
	v_pk_fma_f32 v[124:125], v[4:5], v[68:69], v[52:53]
	v_pk_fma_f32 v[126:127], v[6:7], v[70:71], v[54:55]
	v_pk_fma_f32 v[128:129], v[8:9], v[72:73], v[56:57]
	v_pk_fma_f32 v[214:215], v[10:11], v[74:75], v[58:59]
	v_pk_fma_f32 v[216:217], v[12:13], v[76:77], v[60:61]
	v_pk_fma_f32 v[218:219], v[14:15], v[78:79], v[62:63]
	v_pk_fma_f32 v[220:221], v[16:17], v[80:81], v[64:65]
	v_pk_fma_f32 v[122:123], v[18:19], v[82:83], v[122:123]
	v_pk_fma_f32 v[124:125], v[20:21], v[84:85], v[124:125]
	v_pk_fma_f32 v[126:127], v[22:23], v[86:87], v[126:127]
	v_pk_fma_f32 v[128:129], v[24:25], v[88:89], v[128:129]
	v_pk_fma_f32 v[214:215], v[26:27], v[90:91], v[214:215]
	v_pk_fma_f32 v[216:217], v[28:29], v[92:93], v[216:217]
	v_pk_fma_f32 v[218:219], v[30:31], v[94:95], v[218:219]
	v_pk_fma_f32 v[220:221], v[32:33], v[96:97], v[220:221]
	v_pk_fma_f32 v[122:123], v[34:35], v[98:99], v[122:123]
	v_pk_fma_f32 v[124:125], v[36:37], v[100:101], v[124:125]
	v_pk_fma_f32 v[126:127], v[38:39], v[102:103], v[126:127]
	v_pk_fma_f32 v[128:129], v[40:41], v[104:105], v[128:129]
	v_pk_fma_f32 v[214:215], v[42:43], v[106:107], v[214:215]
	v_pk_fma_f32 v[216:217], v[44:45], v[108:109], v[216:217]
	v_pk_fma_f32 v[218:219], v[46:47], v[110:111], v[218:219]
	v_pk_fma_f32 v[220:221], v[48:49], v[112:113], v[220:221]
	v_mul_f32_e32 v230, v122, v122
	v_mul_f32_e32 v231, v123, v123
	v_mul_f32_e32 v232, v124, v124
	v_mul_f32_e32 v233, v125, v125
	v_mul_f32_e32 v234, v126, v126
	v_mul_f32_e32 v235, v127, v127
	v_mul_f32_e32 v236, v128, v128
	v_mul_f32_e32 v237, v129, v129
	v_fma_f32 v230, v230, s22, v198
	v_fma_f32 v231, v231, s22, v198
	v_fma_f32 v232, v232, s22, v198
	v_fma_f32 v233, v233, s22, v198
	v_fma_f32 v234, v234, s22, v198
	v_fma_f32 v235, v235, s22, v198
	v_fma_f32 v236, v236, s22, v198
	v_fma_f32 v237, v237, s22, v198
	v_mul_f32_e32 v230, v122, v230
	v_mul_f32_e32 v231, v123, v231
	v_mul_f32_e32 v232, v124, v232
	v_mul_f32_e32 v233, v125, v233
	v_mul_f32_e32 v234, v126, v234
	v_mul_f32_e32 v235, v127, v235
	v_mul_f32_e32 v236, v128, v236
	v_mul_f32_e32 v237, v129, v237
	v_exp_f32_e32 v230, v230
	v_exp_f32_e32 v231, v231
	v_exp_f32_e32 v232, v232
	v_exp_f32_e32 v233, v233
	v_exp_f32_e32 v234, v234
	v_exp_f32_e32 v235, v235
	v_exp_f32_e32 v236, v236
	v_exp_f32_e32 v237, v237
	v_add_f32_e32 v230, 1.0, v230
	v_add_f32_e32 v231, 1.0, v231
	v_add_f32_e32 v232, 1.0, v232
	v_add_f32_e32 v233, 1.0, v233
	v_add_f32_e32 v234, 1.0, v234
	v_add_f32_e32 v235, 1.0, v235
	v_add_f32_e32 v236, 1.0, v236
	v_add_f32_e32 v237, 1.0, v237
	v_rcp_f32_e32 v230, v230
	v_rcp_f32_e32 v231, v231
	v_rcp_f32_e32 v232, v232
	v_rcp_f32_e32 v233, v233
	v_rcp_f32_e32 v234, v234
	v_rcp_f32_e32 v235, v235
	v_rcp_f32_e32 v236, v236
	v_rcp_f32_e32 v237, v237
	v_mul_f32_e32 v230, v122, v230
	v_mul_f32_e32 v231, v123, v231
	v_mul_f32_e32 v232, v124, v232
	v_mul_f32_e32 v233, v125, v233
	v_mul_f32_e32 v234, v126, v234
	v_mul_f32_e32 v235, v127, v235
	v_mul_f32_e32 v236, v128, v236
	v_mul_f32_e32 v237, v129, v237
	v_mul_f32_e32 v230, v230, v214
	v_mul_f32_e32 v231, v231, v215
	v_mul_f32_e32 v232, v232, v216
	v_mul_f32_e32 v233, v233, v217
	v_mul_f32_e32 v234, v234, v218
	v_mul_f32_e32 v235, v235, v219
	v_mul_f32_e32 v236, v236, v220
	v_mul_f32_e32 v237, v237, v221
	v_cvt_pk_bf16_f32 v240, v230, v231
	v_cvt_pk_bf16_f32 v241, v232, v233
	v_cvt_pk_bf16_f32 v242, v234, v235
	v_cvt_pk_bf16_f32 v243, v236, v237
	global_store_dwordx4 v144, v[240:243], s[2:3]
	v_add_u32_e32 v144, 0x1600, v144
	s_waitcnt lgkmcnt(0)
; #define GAS __attribute__((address_space(1)))
;     ...
;           for (int h = 0; h < 2; ++h) {
;             const int c16 = h * 16 + ck;
;             float cur[8], p1[8], p2[8];
;             ld8(reinterpret_cast<const u16*>(st + row * 512 + ((c16 ^ (row & 31)) << 4)), cur);
;             if (t >= 1) ld8(reinterpret_cast<const u16*>(st + (row - 1) * 512 + ((c16 ^ ((row - 1) & 31)) << 4)), p1);
;             else if (samp) ld8f(p->cstate + ((size_t)b * 2 + 1) * UPW + ch + h * DFF, p1);
;             else { for (int k = 0; k < 8; ++k) p1[k] = 0.f; }
;             if (t >= 2) ld8(reinterpret_cast<const u16*>(st + (row - 2) * 512 + ((c16 ^ ((row - 2) & 31)) << 4)), p2);
;             else if (samp) ld8f(p->cstate + ((size_t)b * 2 + t) * UPW + ch + h * DFF, p2);
;             else { for (int k = 0; k < 8; ++k) p2[k] = 0.f; }
; #pragma unroll
;             for (int k = 0; k < 8; ++k) {
;               float cv = bb[h][k] + w0[h][k] * p2[k] + w1[h][k] * p1[k] + w2[h][k] * cur[k];
;               if (h == 0) res[k] = gelu_f(cv); else res[k] *= cv;
;             }
;           }
;           *(GAS uint4*)(FI + (size_t)(cur_brow + row) * DFF + ch) =
;               make_uint4(pack2(res[0], res[1]), pack2(res[2], res[3]), pack2(res[4], res[5]), pack2(res[6], res[7]));
	v_lshlrev_b32_e32 v66, 16, v222
	v_and_b32_e32 v67, s21, v222
	v_lshlrev_b32_e32 v68, 16, v223
	v_and_b32_e32 v69, s21, v223
	v_lshlrev_b32_e32 v70, 16, v224
	v_and_b32_e32 v71, s21, v224
	v_lshlrev_b32_e32 v72, 16, v225
	v_and_b32_e32 v73, s21, v225
	v_lshlrev_b32_e32 v74, 16, v226
	v_and_b32_e32 v75, s21, v226
	v_lshlrev_b32_e32 v76, 16, v227
	v_and_b32_e32 v77, s21, v227
	v_lshlrev_b32_e32 v78, 16, v228
	v_and_b32_e32 v79, s21, v228
	v_lshlrev_b32_e32 v80, 16, v229
	v_and_b32_e32 v81, s21, v229
	v_pk_fma_f32 v[122:123], v[2:3], v[82:83], v[50:51]
	v_pk_fma_f32 v[124:125], v[4:5], v[84:85], v[52:53]
	v_pk_fma_f32 v[126:127], v[6:7], v[86:87], v[54:55]
	v_pk_fma_f32 v[128:129], v[8:9], v[88:89], v[56:57]
	v_pk_fma_f32 v[214:215], v[10:11], v[90:91], v[58:59]
	v_pk_fma_f32 v[216:217], v[12:13], v[92:93], v[60:61]
	v_pk_fma_f32 v[218:219], v[14:15], v[94:95], v[62:63]
	v_pk_fma_f32 v[220:221], v[16:17], v[96:97], v[64:65]
	v_pk_fma_f32 v[122:123], v[18:19], v[98:99], v[122:123]
	v_pk_fma_f32 v[124:125], v[20:21], v[100:101], v[124:125]
	v_pk_fma_f32 v[126:127], v[22:23], v[102:103], v[126:127]
	v_pk_fma_f32 v[128:129], v[24:25], v[104:105], v[128:129]
	v_pk_fma_f32 v[214:215], v[26:27], v[106:107], v[214:215]
	v_pk_fma_f32 v[216:217], v[28:29], v[108:109], v[216:217]
	v_pk_fma_f32 v[218:219], v[30:31], v[110:111], v[218:219]
	v_pk_fma_f32 v[220:221], v[32:33], v[112:113], v[220:221]
	v_pk_fma_f32 v[122:123], v[34:35], v[66:67], v[122:123]
	v_pk_fma_f32 v[124:125], v[36:37], v[68:69], v[124:125]
	v_pk_fma_f32 v[126:127], v[38:39], v[70:71], v[126:127]
	v_pk_fma_f32 v[128:129], v[40:41], v[72:73], v[128:129]
	v_pk_fma_f32 v[214:215], v[42:43], v[74:75], v[214:215]
	v_pk_fma_f32 v[216:217], v[44:45], v[76:77], v[216:217]
	v_pk_fma_f32 v[218:219], v[46:47], v[78:79], v[218:219]
	v_pk_fma_f32 v[220:221], v[48:49], v[80:81], v[220:221]
	v_mul_f32_e32 v230, v122, v122
	v_mul_f32_e32 v231, v123, v123
	v_mul_f32_e32 v232, v124, v124
	v_mul_f32_e32 v233, v125, v125
	v_mul_f32_e32 v234, v126, v126
	v_mul_f32_e32 v235, v127, v127
	v_mul_f32_e32 v236, v128, v128
	v_mul_f32_e32 v237, v129, v129
	v_fma_f32 v230, v230, s22, v198
	v_fma_f32 v231, v231, s22, v198
	v_fma_f32 v232, v232, s22, v198
	v_fma_f32 v233, v233, s22, v198
	v_fma_f32 v234, v234, s22, v198
	v_fma_f32 v235, v235, s22, v198
	v_fma_f32 v236, v236, s22, v198
	v_fma_f32 v237, v237, s22, v198
	v_mul_f32_e32 v230, v122, v230
	v_mul_f32_e32 v231, v123, v231
	v_mul_f32_e32 v232, v124, v232
	v_mul_f32_e32 v233, v125, v233
	v_mul_f32_e32 v234, v126, v234
	v_mul_f32_e32 v235, v127, v235
	v_mul_f32_e32 v236, v128, v236
	v_mul_f32_e32 v237, v129, v237
	v_exp_f32_e32 v230, v230
	v_exp_f32_e32 v231, v231
	v_exp_f32_e32 v232, v232
	v_exp_f32_e32 v233, v233
	v_exp_f32_e32 v234, v234
	v_exp_f32_e32 v235, v235
	v_exp_f32_e32 v236, v236
	v_exp_f32_e32 v237, v237
	v_add_f32_e32 v230, 1.0, v230
	v_add_f32_e32 v231, 1.0, v231
	v_add_f32_e32 v232, 1.0, v232
	v_add_f32_e32 v233, 1.0, v233
	v_add_f32_e32 v234, 1.0, v234
	v_add_f32_e32 v235, 1.0, v235
	v_add_f32_e32 v236, 1.0, v236
	v_add_f32_e32 v237, 1.0, v237
	v_rcp_f32_e32 v230, v230
	v_rcp_f32_e32 v231, v231
	v_rcp_f32_e32 v232, v232
	v_rcp_f32_e32 v233, v233
	v_rcp_f32_e32 v234, v234
	v_rcp_f32_e32 v235, v235
	v_rcp_f32_e32 v236, v236
	v_rcp_f32_e32 v237, v237
	v_mul_f32_e32 v230, v122, v230
	v_mul_f32_e32 v231, v123, v231
	v_mul_f32_e32 v232, v124, v232
	v_mul_f32_e32 v233, v125, v233
	v_mul_f32_e32 v234, v126, v234
	v_mul_f32_e32 v235, v127, v235
	v_mul_f32_e32 v236, v128, v236
	v_mul_f32_e32 v237, v129, v237
	v_mul_f32_e32 v230, v230, v214
	v_mul_f32_e32 v231, v231, v215
	v_mul_f32_e32 v232, v232, v216
	v_mul_f32_e32 v233, v233, v217
	v_mul_f32_e32 v234, v234, v218
	v_mul_f32_e32 v235, v235, v219
	v_mul_f32_e32 v236, v236, v220
	v_mul_f32_e32 v237, v237, v221
	v_cvt_pk_bf16_f32 v240, v230, v231
	v_cvt_pk_bf16_f32 v241, v232, v233
	v_cvt_pk_bf16_f32 v242, v234, v235
	v_cvt_pk_bf16_f32 v243, v236, v237
	global_store_dwordx4 v144, v[240:243], s[2:3]
	s_branch .LBB0_1246
